# RMSNorm row loops (layer-0 input norm, final norm): eight row loads issued together with counted waits
# baseline (speedup 1.0000x reference)
; DI void phase_rmsnorm(const float* src, const float* g, bf16_t* dst, float* fout) {
;     ...
;   for (int row = blockIdx.x * 8 + wid; row < T_TOK; row += gridDim.x * 8) {
;     const float* p = src + (size_t)row * DM;
;     f32x4 v[8]; float ss = 0.f;
; #pragma unroll
;     for (int j = 0; j < 8; ++j) { v[j] = *(const f32x4*)(p + (j * 64 + lane) * 4); ss += v[j][0] * v[j][0] + v[j][1] * v[j][1] + v[j][2] * v[j][2] + v[j][3] * v[j][3]; }
;     ss = wave_sum(ss);
;     const float rs = rsqrtf(ss * (1.f / DM) + 1e-6f);
;     if (fout) {
; #pragma unroll
;       for (int j = 0; j < 8; ++j) *(f32x4*)(fout + (size_t)row * DM + (j * 64 + lane) * 4) = v[j] * rs * gv[j];
.LBB0_22:
	v_ashrrev_i32_e32 v67, 31, v66
	v_lshlrev_b64 v[34:35], 13, v[66:67]
	v_lshl_add_u64 v[54:55], s[42:43], 0, v[34:35]
	v_lshl_add_u64 v[78:79], v[54:55], 0, v[0:1]
	v_mov_b32_e32 v71, v1
	v_lshl_add_u64 v[82:83], v[54:55], 0, v[70:71]
	v_mov_b32_e32 v73, v1
	v_lshl_add_u64 v[80:81], v[54:55], 0, v[72:73]
	v_mov_b32_e32 v75, v1
	v_mov_b32_e32 v77, v1
	v_lshl_add_u64 v[86:87], v[54:55], 0, v[74:75]
	v_lshl_add_u64 v[84:85], v[54:55], 0, v[76:77]
	global_load_dwordx4 v[62:65], v[78:79], off
	global_load_dwordx4 v[34:37], v[78:79], off offset:1024
	global_load_dwordx4 v[38:41], v[78:79], off offset:2048
	global_load_dwordx4 v[42:45], v[78:79], off offset:3072
	global_load_dwordx4 v[50:53], v[82:83], off
	global_load_dwordx4 v[46:49], v[80:81], off
	global_load_dwordx4 v[58:61], v[86:87], off
	global_load_dwordx4 v[54:57], v[84:85], off
	s_waitcnt vmcnt(7)
	v_mul_f32_e32 v88, v62, v62
	v_fmac_f32_e32 v88, v63, v63
	v_fmac_f32_e32 v88, v64, v64
	v_fmac_f32_e32 v88, v65, v65
	s_waitcnt vmcnt(6)
	v_mul_f32_e32 v89, v34, v34
	v_fmac_f32_e32 v89, v35, v35
	v_fmac_f32_e32 v89, v36, v36
	v_fmac_f32_e32 v89, v37, v37
	s_waitcnt vmcnt(5)
	v_fmac_f32_e32 v88, v38, v38
	v_fmac_f32_e32 v88, v39, v39
	v_fmac_f32_e32 v88, v40, v40
	v_fmac_f32_e32 v88, v41, v41
	s_waitcnt vmcnt(4)
	v_fmac_f32_e32 v89, v42, v42
	v_fmac_f32_e32 v89, v43, v43
	v_fmac_f32_e32 v89, v44, v44
	v_fmac_f32_e32 v89, v45, v45
	s_waitcnt vmcnt(3)
	v_fmac_f32_e32 v88, v50, v50
	v_fmac_f32_e32 v88, v51, v51
	v_fmac_f32_e32 v88, v52, v52
	v_fmac_f32_e32 v88, v53, v53
	s_waitcnt vmcnt(2)
	v_fmac_f32_e32 v89, v46, v46
	v_fmac_f32_e32 v89, v47, v47
	v_fmac_f32_e32 v89, v48, v48
	v_fmac_f32_e32 v89, v49, v49
	s_waitcnt vmcnt(1)
	v_fmac_f32_e32 v88, v58, v58
	v_fmac_f32_e32 v88, v59, v59
	v_fmac_f32_e32 v88, v60, v60
	v_fmac_f32_e32 v88, v61, v61
	s_waitcnt vmcnt(0)
	v_fmac_f32_e32 v89, v54, v54
	v_fmac_f32_e32 v89, v55, v55
	v_fmac_f32_e32 v89, v56, v56
	v_fmac_f32_e32 v89, v57, v57
	v_add_f32_e32 v71, v88, v89
	ds_bpermute_b32 v73, v96, v71
	s_waitcnt lgkmcnt(0)
	v_add_f32_e32 v71, v71, v73
	ds_bpermute_b32 v73, v97, v71
	s_waitcnt lgkmcnt(0)
	v_add_f32_e32 v71, v71, v73
	ds_bpermute_b32 v73, v98, v71
	s_waitcnt lgkmcnt(0)
	v_add_f32_e32 v71, v71, v73
	ds_bpermute_b32 v73, v99, v71
	s_waitcnt lgkmcnt(0)
	v_add_f32_e32 v71, v71, v73
	ds_bpermute_b32 v73, v100, v71
	s_waitcnt lgkmcnt(0)
	v_add_f32_e32 v71, v71, v73
	ds_bpermute_b32 v73, v101, v71
	s_waitcnt lgkmcnt(0)
	v_add_f32_e32 v71, v71, v73
	v_fmamk_f32 v71, v71, 0x3a000000, v162
	v_cmp_gt_f32_e32 vcc, s2, v71
	v_mul_f32_e32 v73, 0x4b800000, v71
	s_nop 0
	v_cndmask_b32_e32 v71, v71, v73, vcc
	v_rsq_f32_e32 v71, v71
	s_nop 0
	v_mul_f32_e32 v73, 0x45800000, v71
	v_cndmask_b32_e32 v88, v71, v73, vcc
	v_mov_b32_e32 v89, v88
	v_pk_mul_f32 v[62:63], v[62:63], v[88:89] op_sel_hi:[1,0]
	v_pk_mul_f32 v[64:65], v[64:65], v[88:89] op_sel_hi:[1,0]
	v_pk_mul_f32 v[62:63], v[2:3], v[62:63]
	v_pk_mul_f32 v[64:65], v[4:5], v[64:65]
	s_andn2_b64 vcc, exec, s[10:11]
	v_pk_mul_f32 v[94:95], v[34:35], v[88:89]
	v_pk_mul_f32 v[92:93], v[38:39], v[88:89]
	v_pk_mul_f32 v[90:91], v[42:43], v[88:89]
	v_pk_mul_f32 v[50:51], v[50:51], v[88:89]
	v_pk_mul_f32 v[42:43], v[46:47], v[88:89]
	v_pk_mul_f32 v[38:39], v[58:59], v[88:89]
	v_pk_mul_f32 v[34:35], v[54:55], v[88:89]
	s_cbranch_vccnz .LBB0_24
	v_mov_b32_e32 v89, v88
	v_pk_mul_f32 v[46:47], v[36:37], v[88:89]
	v_pk_mul_f32 v[102:103], v[6:7], v[94:95]
	v_pk_mul_f32 v[104:105], v[8:9], v[46:47]
	v_pk_mul_f32 v[46:47], v[40:41], v[88:89]
	global_store_dwordx4 v[78:79], v[102:105], off offset:1024
	global_store_dwordx4 v[78:79], v[62:65], off
	s_nop 0
	v_pk_mul_f32 v[104:105], v[12:13], v[46:47]
	v_pk_mul_f32 v[102:103], v[10:11], v[92:93]
	v_pk_mul_f32 v[46:47], v[44:45], v[88:89]
	global_store_dwordx4 v[78:79], v[102:105], off offset:2048
	s_nop 1
	v_pk_mul_f32 v[104:105], v[16:17], v[46:47]
	v_pk_mul_f32 v[102:103], v[14:15], v[90:91]
	v_pk_mul_f32 v[46:47], v[52:53], v[88:89]
	global_store_dwordx4 v[78:79], v[102:105], off offset:3072
	v_pk_mul_f32 v[78:79], v[26:27], v[38:39]
	s_nop 0
	v_pk_mul_f32 v[104:105], v[20:21], v[46:47]
	v_pk_mul_f32 v[102:103], v[18:19], v[50:51]
	v_pk_mul_f32 v[46:47], v[48:49], v[88:89]
	global_store_dwordx4 v[82:83], v[102:105], off
	s_nop 1
	v_pk_mul_f32 v[104:105], v[24:25], v[46:47]
	v_pk_mul_f32 v[102:103], v[22:23], v[42:43]
	v_pk_mul_f32 v[46:47], v[60:61], v[88:89]
	global_store_dwordx4 v[80:81], v[102:105], off
	v_pk_mul_f32 v[80:81], v[28:29], v[46:47]
	v_pk_mul_f32 v[46:47], v[56:57], v[88:89]
	global_store_dwordx4 v[86:87], v[78:81], off
	s_nop 1
	v_pk_mul_f32 v[80:81], v[32:33], v[46:47]
	v_pk_mul_f32 v[78:79], v[30:31], v[34:35]
	global_store_dwordx4 v[84:85], v[78:81], off
	s_cbranch_execnz .LBB0_21
	s_branch .LBB0_25

; DI unsigned cvt_pk_bf16(float lo, float hi) { unsigned r; asm volatile("v_cvt_pk_bf16_f32 %0, %1, %2" : "=v"(r) : "v"(lo), "v"(hi)); return r; }
; DI void phase_rmsnorm(const float* src, const float* g, bf16_t* dst, float* fout) {
;     ...
;   for (int row = blockIdx.x * 8 + wid; row < T_TOK; row += gridDim.x * 8) {
;     const float* p = src + (size_t)row * DM;
;     f32x4 v[8]; float ss = 0.f;
; #pragma unroll
;     for (int j = 0; j < 8; ++j) { v[j] = *(const f32x4*)(p + (j * 64 + lane) * 4); ss += v[j][0] * v[j][0] + v[j][1] * v[j][1] + v[j][2] * v[j][2] + v[j][3] * v[j][3]; }
;     ss = wave_sum(ss);
;     const float rs = rsqrtf(ss * (1.f / DM) + 1e-6f);
;     if (fout) {
; #pragma unroll
;       for (int j = 0; j < 8; ++j) *(f32x4*)(fout + (size_t)row * DM + (j * 64 + lane) * 4) = v[j] * rs * gv[j];
;     } else {
; #pragma unroll
;       for (int j = 0; j < 8; ++j) { const f32x4 o = v[j] * rs * gv[j]; u32x2 w; w.x = cvt_pk_bf16(o[0], o[1]); w.y = cvt_pk_bf16(o[2], o[3]); *(u32x2*)(dst + (size_t)row * DM + (j * 64 + lane) * 4) = w; }
.LBB0_296:
	s_load_dwordx2 s[8:9], s[0:1], 0x0
	v_ashrrev_i32_e32 v67, 31, v66
	v_lshlrev_b64 v[34:35], 13, v[66:67]
	v_mov_b32_e32 v73, v1
	v_mov_b32_e32 v71, v1
	s_waitcnt lgkmcnt(0)
	v_lshl_add_u64 v[62:63], s[8:9], 0, v[34:35]
	v_lshl_add_u64 v[42:43], v[62:63], 0, v[0:1]
	v_mov_b32_e32 v86, 0x1000
	v_mov_b32_e32 v87, v1
	v_lshl_add_u64 v[84:85], v[42:43], 0, v[86:87]
	global_load_dwordx4 v[46:49], v[42:43], off
	global_load_dwordx4 v[34:37], v[42:43], off offset:1024
	global_load_dwordx4 v[38:41], v[42:43], off offset:2048
	global_load_dwordx4 v[50:53], v[84:85], off
	global_load_dwordx4 v[54:57], v[84:85], off offset:1024
	global_load_dwordx4 v[58:61], v[84:85], off offset:2048
	global_load_dwordx4 v[62:65], v[84:85], off offset:3072
	global_load_dwordx4 v[42:45], v[42:43], off offset:3072
	s_waitcnt vmcnt(7)
	v_mul_f32_e32 v86, v46, v46
	v_fmac_f32_e32 v86, v47, v47
	v_fmac_f32_e32 v86, v48, v48
	v_fmac_f32_e32 v86, v49, v49
	s_waitcnt vmcnt(6)
	v_mul_f32_e32 v87, v34, v34
	v_fmac_f32_e32 v87, v35, v35
	v_fmac_f32_e32 v87, v36, v36
	v_fmac_f32_e32 v87, v37, v37
	s_waitcnt vmcnt(5)
	v_fmac_f32_e32 v86, v38, v38
	v_fmac_f32_e32 v86, v39, v39
	v_fmac_f32_e32 v86, v40, v40
	v_fmac_f32_e32 v86, v41, v41
	s_waitcnt vmcnt(4)
	v_fmac_f32_e32 v87, v50, v50
	v_fmac_f32_e32 v87, v51, v51
	v_fmac_f32_e32 v87, v52, v52
	v_fmac_f32_e32 v87, v53, v53
	s_waitcnt vmcnt(3)
	v_fmac_f32_e32 v86, v54, v54
	v_fmac_f32_e32 v86, v55, v55
	v_fmac_f32_e32 v86, v56, v56
	v_fmac_f32_e32 v86, v57, v57
	s_waitcnt vmcnt(2)
	v_fmac_f32_e32 v87, v58, v58
	v_fmac_f32_e32 v87, v59, v59
	v_fmac_f32_e32 v87, v60, v60
	v_fmac_f32_e32 v87, v61, v61
	s_waitcnt vmcnt(1)
	v_fmac_f32_e32 v86, v62, v62
	v_fmac_f32_e32 v86, v63, v63
	v_fmac_f32_e32 v86, v64, v64
	v_fmac_f32_e32 v86, v65, v65
	s_waitcnt vmcnt(0)
	v_fmac_f32_e32 v87, v42, v42
	v_fmac_f32_e32 v87, v43, v43
	v_fmac_f32_e32 v87, v44, v44
	v_fmac_f32_e32 v87, v45, v45
	v_add_f32_e32 v71, v86, v87
	ds_bpermute_b32 v73, v78, v71
	s_waitcnt lgkmcnt(0)
	v_add_f32_e32 v71, v71, v73
	ds_bpermute_b32 v73, v79, v71
	s_waitcnt lgkmcnt(0)
	v_add_f32_e32 v71, v71, v73
	ds_bpermute_b32 v73, v80, v71
	s_waitcnt lgkmcnt(0)
	v_add_f32_e32 v71, v71, v73
	ds_bpermute_b32 v73, v81, v71
	s_waitcnt lgkmcnt(0)
	v_add_f32_e32 v71, v71, v73
	ds_bpermute_b32 v73, v82, v71
	s_waitcnt lgkmcnt(0)
	v_add_f32_e32 v71, v71, v73
	ds_bpermute_b32 v73, v83, v71
	s_waitcnt lgkmcnt(0)
	v_add_f32_e32 v71, v71, v73
	v_fmamk_f32 v71, v71, 0x3a000000, v162
	v_cmp_gt_f32_e32 vcc, s2, v71
	v_mul_f32_e32 v73, 0x4b800000, v71
	s_nop 0
	v_cndmask_b32_e32 v71, v71, v73, vcc
	v_rsq_f32_e32 v71, v71
	s_nop 0
	v_mul_f32_e32 v73, 0x45800000, v71
	v_cndmask_b32_e32 v84, v71, v73, vcc
	v_pk_mul_f32 v[46:47], v[46:47], v[84:85] op_sel_hi:[1,0]
	v_pk_mul_f32 v[48:49], v[48:49], v[84:85] op_sel_hi:[1,0]
	v_pk_mul_f32 v[46:47], v[2:3], v[46:47]
	v_pk_mul_f32 v[48:49], v[4:5], v[48:49]
	v_cvt_pk_bf16_f32 v46, v46, v47
	v_pk_mul_f32 v[34:35], v[34:35], v[84:85] op_sel_hi:[1,0]
	v_cvt_pk_bf16_f32 v47, v48, v49
	v_lshlrev_b64 v[48:49], 12, v[66:67]
	v_lshl_add_u64 v[48:49], v[68:69], 0, v[48:49]
	v_pk_mul_f32 v[36:37], v[36:37], v[84:85] op_sel_hi:[1,0]
	v_pk_mul_f32 v[34:35], v[6:7], v[34:35]
	global_store_dwordx2 v[48:49], v[46:47], off
	v_pk_mul_f32 v[36:37], v[8:9], v[36:37]
	v_cvt_pk_bf16_f32 v34, v34, v35
	v_add_u32_e32 v66, s3, v66
	v_cvt_pk_bf16_f32 v35, v36, v37
	global_store_dwordx2 v[48:49], v[34:35], off offset:512
	v_pk_mul_f32 v[34:35], v[38:39], v[84:85] op_sel_hi:[1,0]
	v_pk_mul_f32 v[36:37], v[40:41], v[84:85] op_sel_hi:[1,0]
	v_pk_mul_f32 v[34:35], v[10:11], v[34:35]
	v_pk_mul_f32 v[36:37], v[12:13], v[36:37]
	v_cvt_pk_bf16_f32 v34, v34, v35
	v_cmp_lt_i32_e32 vcc, s79, v66
	v_cvt_pk_bf16_f32 v35, v36, v37
	global_store_dwordx2 v[48:49], v[34:35], off offset:1024
	v_pk_mul_f32 v[34:35], v[42:43], v[84:85] op_sel_hi:[1,0]
	v_pk_mul_f32 v[36:37], v[44:45], v[84:85] op_sel_hi:[1,0]
	v_pk_mul_f32 v[34:35], v[14:15], v[34:35]
	v_pk_mul_f32 v[36:37], v[16:17], v[36:37]
	v_cvt_pk_bf16_f32 v34, v34, v35
	s_or_b64 s[6:7], vcc, s[6:7]
	v_cvt_pk_bf16_f32 v35, v36, v37
	global_store_dwordx2 v[48:49], v[34:35], off offset:1536
	v_pk_mul_f32 v[34:35], v[50:51], v[84:85] op_sel_hi:[1,0]
	v_pk_mul_f32 v[36:37], v[52:53], v[84:85] op_sel_hi:[1,0]
	v_pk_mul_f32 v[34:35], v[18:19], v[34:35]
	v_pk_mul_f32 v[36:37], v[20:21], v[36:37]
	v_cvt_pk_bf16_f32 v34, v34, v35
	s_nop 0
	v_cvt_pk_bf16_f32 v35, v36, v37
	global_store_dwordx2 v[48:49], v[34:35], off offset:2048
	v_pk_mul_f32 v[34:35], v[54:55], v[84:85] op_sel_hi:[1,0]
	v_pk_mul_f32 v[36:37], v[56:57], v[84:85] op_sel_hi:[1,0]
	v_pk_mul_f32 v[34:35], v[22:23], v[34:35]
	v_pk_mul_f32 v[36:37], v[24:25], v[36:37]
	v_cvt_pk_bf16_f32 v34, v34, v35
	s_nop 0
	v_cvt_pk_bf16_f32 v35, v36, v37
	global_store_dwordx2 v[48:49], v[34:35], off offset:2560
	v_pk_mul_f32 v[34:35], v[58:59], v[84:85] op_sel_hi:[1,0]
	v_pk_mul_f32 v[36:37], v[60:61], v[84:85] op_sel_hi:[1,0]
	v_pk_mul_f32 v[34:35], v[26:27], v[34:35]
	v_pk_mul_f32 v[36:37], v[28:29], v[36:37]
	v_cvt_pk_bf16_f32 v34, v34, v35
	s_nop 0
	v_cvt_pk_bf16_f32 v35, v36, v37
	global_store_dwordx2 v[48:49], v[34:35], off offset:3072
	v_pk_mul_f32 v[34:35], v[62:63], v[84:85] op_sel_hi:[1,0]
	v_pk_mul_f32 v[36:37], v[64:65], v[84:85] op_sel_hi:[1,0]
	v_pk_mul_f32 v[34:35], v[30:31], v[34:35]
	v_pk_mul_f32 v[36:37], v[32:33], v[36:37]
	v_cvt_pk_bf16_f32 v34, v34, v35
	s_nop 0
	v_cvt_pk_bf16_f32 v35, v36, v37
	global_store_dwordx2 v[48:49], v[34:35], off offset:3584
	s_andn2_b64 exec, exec, s[6:7]
	s_cbranch_execnz .LBB0_296
